# v39 + window-cache output copy moved from the layer-1 up-proj window to the ML-in idle window
# speedup vs baseline: 1.0067x; 1.0002x over previous
.Lcv3_done:
	v_readlane_b32 s2, v200, 0
	v_readlane_b32 s3, v200, 1
	v_readlane_b32 s4, v200, 2
	v_readlane_b32 s5, v200, 3
	v_readlane_b32 s6, v200, 4
	v_readlane_b32 s7, v200, 5
	v_readlane_b32 s8, v200, 6
	v_readlane_b32 s9, v200, 7
	v_readlane_b32 s10, v200, 8
	v_readlane_b32 s11, v200, 9
	v_readlane_b32 s12, v200, 10
	v_readlane_b32 s13, v200, 11
	v_readlane_b32 s14, v200, 12
	v_readlane_b32 s15, v200, 13
	v_readlane_b32 s16, v200, 14
	v_readlane_b32 s17, v200, 15
	v_readlane_b32 s18, v200, 16
	v_readlane_b32 s19, v200, 17
	v_readlane_b32 s20, v200, 18
	v_readlane_b32 s21, v200, 19
	v_readlane_b32 s22, v200, 20
	v_readlane_b32 s23, v200, 21
	v_readlane_b32 s24, v200, 22
	v_readlane_b32 s25, v200, 23
	v_readlane_b32 s26, v200, 24
	v_readlane_b32 s27, v200, 25
	v_readlane_b32 s28, v200, 26
	v_readlane_b32 s29, v200, 27
	v_readlane_b32 s30, v200, 28
	v_readlane_b32 s31, v200, 29
	v_readlane_b32 s32, v200, 30
	v_readlane_b32 s33, v200, 31
	v_readlane_b32 s34, v200, 32
	v_readlane_b32 s35, v200, 33
	v_readlane_b32 s36, v200, 34
	v_readlane_b32 s37, v200, 35
	v_readlane_b32 s38, v200, 36
	v_readlane_b32 s39, v200, 37
	v_readlane_b32 s40, v200, 38
	v_readlane_b32 s41, v200, 39
	v_readlane_b32 s42, v200, 40
	v_readlane_b32 s43, v200, 41
	v_readlane_b32 s44, v200, 42
	v_readlane_b32 s45, v200, 43
	v_readlane_b32 s46, v200, 44
	v_readlane_b32 s47, v200, 45
	v_readlane_b32 s48, v200, 46
	v_readlane_b32 s49, v200, 47
	v_readlane_b32 s50, v200, 48
	v_readlane_b32 s51, v200, 49
	v_readlane_b32 s52, v200, 50
	v_readlane_b32 s53, v200, 51
	v_readlane_b32 s54, v200, 52
	v_readlane_b32 s55, v200, 53
	v_readlane_b32 s56, v200, 54
	v_readlane_b32 s57, v200, 55
	v_readlane_b32 s58, v200, 56
	v_readlane_b32 s59, v200, 57
	v_readlane_b32 s60, v200, 58
	v_readlane_b32 s61, v200, 59
	v_readlane_b32 s62, v200, 60
	v_readlane_b32 s63, v200, 61
	v_readlane_b32 s64, v200, 62
	v_readlane_b32 s65, v200, 63
	v_readlane_b32 s66, v201, 0
	v_readlane_b32 s67, v201, 1
	v_readlane_b32 s68, v201, 2
	v_readlane_b32 s69, v201, 3
	v_readlane_b32 s70, v201, 4
	v_readlane_b32 s71, v201, 5
	v_readlane_b32 s72, v201, 6
	v_readlane_b32 s73, v201, 7
	v_readlane_b32 s74, v201, 8
	v_readlane_b32 s75, v201, 9
	v_readlane_b32 s76, v201, 10
	v_readlane_b32 s77, v201, 11
	v_readlane_b32 s78, v201, 12
	v_readlane_b32 s79, v201, 13
	v_readlane_b32 s80, v201, 14
	v_readlane_b32 s81, v201, 15
	v_readlane_b32 s82, v201, 16
	v_readlane_b32 s83, v201, 17
	v_readlane_b32 s84, v201, 18
	v_readlane_b32 s85, v201, 19
	v_readlane_b32 s86, v201, 20
	v_readlane_b32 s87, v201, 21
	v_readlane_b32 s88, v201, 22
	v_readlane_b32 s89, v201, 23
	v_readlane_b32 s90, v201, 24
	v_readlane_b32 s91, v201, 25
	v_readlane_b32 s92, v201, 26
	v_readlane_b32 s93, v201, 27
	v_readlane_b32 s94, v201, 28
	v_readlane_b32 s95, v201, 29
	v_readlane_b32 s96, v201, 30
	v_readlane_b32 s97, v201, 31
	v_readlane_b32 s98, v201, 32
	v_readlane_b32 s99, v201, 33
	v_readlane_b32 s101, v254, 19
	v_writelane_b32 v200, s2, 0
	v_writelane_b32 v200, s3, 1
	v_writelane_b32 v200, s4, 2
	v_writelane_b32 v200, s5, 3
	v_writelane_b32 v200, s6, 4
	v_writelane_b32 v200, s7, 5
	v_writelane_b32 v200, s8, 6
	v_writelane_b32 v200, s9, 7
	v_writelane_b32 v200, s10, 8
	v_writelane_b32 v200, s11, 9
	v_writelane_b32 v200, s12, 10
	v_writelane_b32 v200, s13, 11
	v_writelane_b32 v200, s14, 12
	v_writelane_b32 v200, s15, 13
	s_load_dwordx2 s[10:11], s[0:1], 0x18
	s_load_dwordx2 s[6:7], s[0:1], 0xb8
	v_mbcnt_lo_u32_b32 v0, -1, 0
	v_mbcnt_hi_u32_b32 v0, -1, v0
	v_readlane_b32 s4, v255, 4
	s_nop 1
	v_lshl_add_u32 v0, s4, 6, v0
	s_sub_i32 s4, s101, 77
	s_lshl_b32 s4, s4, 9
	v_or_b32_e32 v2, s4, v0
	s_mov_b32 s8, 0x16600
	s_mov_b32 s3, 0x2040811
	s_mov_b32 s12, 0x1fbfff
	s_waitcnt lgkmcnt(0)
	s_add_u32 s6, s6, 0x8500000
	s_addc_u32 s7, s7, 0
	s_add_u32 s10, s10, 0x2000
	s_addc_u32 s11, s11, 0
	v_min_u32_e32 v4, s12, v2
	v_add_u32_e32 v2, s8, v2
	v_min_u32_e32 v5, s12, v2
	v_add_u32_e32 v2, s8, v2
	v_min_u32_e32 v6, s12, v2
	v_add_u32_e32 v2, s8, v2
	v_min_u32_e32 v7, s12, v2
	v_add_u32_e32 v2, s8, v2
	v_min_u32_e32 v8, s12, v2
	v_add_u32_e32 v2, s8, v2
	v_min_u32_e32 v9, s12, v2
	v_add_u32_e32 v2, s8, v2
	v_min_u32_e32 v10, s12, v2
	v_add_u32_e32 v2, s8, v2
	v_min_u32_e32 v11, s12, v2
	v_add_u32_e32 v2, s8, v2
	v_lshrrev_b32_e32 v12, 9, v4
	v_mul_hi_u32 v12, v12, s3
	v_mul_u32_u24_e32 v13, 0xfe00, v12
	v_sub_u32_e32 v13, v4, v13
	v_lshlrev_b32_e32 v12, 20, v12
	v_lshl_add_u32 v4, v13, 4, v12
	global_load_dwordx4 v[32:35], v4, s[10:11]
	v_lshrrev_b32_e32 v12, 9, v5
	v_mul_hi_u32 v12, v12, s3
	v_mul_u32_u24_e32 v13, 0xfe00, v12
	v_sub_u32_e32 v13, v5, v13
	v_lshlrev_b32_e32 v12, 20, v12
	v_lshl_add_u32 v5, v13, 4, v12
	global_load_dwordx4 v[36:39], v5, s[10:11]
	v_lshrrev_b32_e32 v12, 9, v6
	v_mul_hi_u32 v12, v12, s3
	v_mul_u32_u24_e32 v13, 0xfe00, v12
	v_sub_u32_e32 v13, v6, v13
	v_lshlrev_b32_e32 v12, 20, v12
	v_lshl_add_u32 v6, v13, 4, v12
	global_load_dwordx4 v[40:43], v6, s[10:11]
	v_lshrrev_b32_e32 v12, 9, v7
	v_mul_hi_u32 v12, v12, s3
	v_mul_u32_u24_e32 v13, 0xfe00, v12
	v_sub_u32_e32 v13, v7, v13
	v_lshlrev_b32_e32 v12, 20, v12
	v_lshl_add_u32 v7, v13, 4, v12
	global_load_dwordx4 v[44:47], v7, s[10:11]
	v_lshrrev_b32_e32 v12, 9, v8
	v_mul_hi_u32 v12, v12, s3
	v_mul_u32_u24_e32 v13, 0xfe00, v12
	v_sub_u32_e32 v13, v8, v13
	v_lshlrev_b32_e32 v12, 20, v12
	v_lshl_add_u32 v8, v13, 4, v12
	global_load_dwordx4 v[48:51], v8, s[10:11]
	v_lshrrev_b32_e32 v12, 9, v9
	v_mul_hi_u32 v12, v12, s3
	v_mul_u32_u24_e32 v13, 0xfe00, v12
	v_sub_u32_e32 v13, v9, v13
	v_lshlrev_b32_e32 v12, 20, v12
	v_lshl_add_u32 v9, v13, 4, v12
	global_load_dwordx4 v[52:55], v9, s[10:11]
	v_lshrrev_b32_e32 v12, 9, v10
	v_mul_hi_u32 v12, v12, s3
	v_mul_u32_u24_e32 v13, 0xfe00, v12
	v_sub_u32_e32 v13, v10, v13
	v_lshlrev_b32_e32 v12, 20, v12
	v_lshl_add_u32 v10, v13, 4, v12
	global_load_dwordx4 v[56:59], v10, s[10:11]
	v_lshrrev_b32_e32 v12, 9, v11
	v_mul_hi_u32 v12, v12, s3
	v_mul_u32_u24_e32 v13, 0xfe00, v12
	v_sub_u32_e32 v13, v11, v13
	v_lshlrev_b32_e32 v12, 20, v12
	v_lshl_add_u32 v11, v13, 4, v12
	global_load_dwordx4 v[60:63], v11, s[10:11]
	s_waitcnt vmcnt(0)
	global_store_dwordx4 v4, v[32:35], s[6:7]
	global_store_dwordx4 v5, v[36:39], s[6:7]
	global_store_dwordx4 v6, v[40:43], s[6:7]
	global_store_dwordx4 v7, v[44:47], s[6:7]
	global_store_dwordx4 v8, v[48:51], s[6:7]
	global_store_dwordx4 v9, v[52:55], s[6:7]
	global_store_dwordx4 v10, v[56:59], s[6:7]
	global_store_dwordx4 v11, v[60:63], s[6:7]
	s_nop 1
	v_min_u32_e32 v4, s12, v2
	v_add_u32_e32 v2, s8, v2
	v_min_u32_e32 v5, s12, v2
	v_add_u32_e32 v2, s8, v2
	v_min_u32_e32 v6, s12, v2
	v_add_u32_e32 v2, s8, v2
	v_min_u32_e32 v7, s12, v2
	v_add_u32_e32 v2, s8, v2
	v_min_u32_e32 v8, s12, v2
	v_add_u32_e32 v2, s8, v2
	v_min_u32_e32 v9, s12, v2
	v_add_u32_e32 v2, s8, v2
	v_min_u32_e32 v10, s12, v2
	v_add_u32_e32 v2, s8, v2
	v_min_u32_e32 v11, s12, v2
	v_add_u32_e32 v2, s8, v2
	v_lshrrev_b32_e32 v12, 9, v4
	v_mul_hi_u32 v12, v12, s3
	v_mul_u32_u24_e32 v13, 0xfe00, v12
	v_sub_u32_e32 v13, v4, v13
	v_lshlrev_b32_e32 v12, 20, v12
	v_lshl_add_u32 v4, v13, 4, v12
	global_load_dwordx4 v[32:35], v4, s[10:11]
	v_lshrrev_b32_e32 v12, 9, v5
	v_mul_hi_u32 v12, v12, s3
	v_mul_u32_u24_e32 v13, 0xfe00, v12
	v_sub_u32_e32 v13, v5, v13
	v_lshlrev_b32_e32 v12, 20, v12
	v_lshl_add_u32 v5, v13, 4, v12
	global_load_dwordx4 v[36:39], v5, s[10:11]
	v_lshrrev_b32_e32 v12, 9, v6
	v_mul_hi_u32 v12, v12, s3
	v_mul_u32_u24_e32 v13, 0xfe00, v12
	v_sub_u32_e32 v13, v6, v13
	v_lshlrev_b32_e32 v12, 20, v12
	v_lshl_add_u32 v6, v13, 4, v12
	global_load_dwordx4 v[40:43], v6, s[10:11]
	v_lshrrev_b32_e32 v12, 9, v7
	v_mul_hi_u32 v12, v12, s3
	v_mul_u32_u24_e32 v13, 0xfe00, v12
	v_sub_u32_e32 v13, v7, v13
	v_lshlrev_b32_e32 v12, 20, v12
	v_lshl_add_u32 v7, v13, 4, v12
	global_load_dwordx4 v[44:47], v7, s[10:11]
	v_lshrrev_b32_e32 v12, 9, v8
	v_mul_hi_u32 v12, v12, s3
	v_mul_u32_u24_e32 v13, 0xfe00, v12
	v_sub_u32_e32 v13, v8, v13
	v_lshlrev_b32_e32 v12, 20, v12
	v_lshl_add_u32 v8, v13, 4, v12
	global_load_dwordx4 v[48:51], v8, s[10:11]
	v_lshrrev_b32_e32 v12, 9, v9
	v_mul_hi_u32 v12, v12, s3
	v_mul_u32_u24_e32 v13, 0xfe00, v12
	v_sub_u32_e32 v13, v9, v13
	v_lshlrev_b32_e32 v12, 20, v12
	v_lshl_add_u32 v9, v13, 4, v12
	global_load_dwordx4 v[52:55], v9, s[10:11]
	v_lshrrev_b32_e32 v12, 9, v10
	v_mul_hi_u32 v12, v12, s3
	v_mul_u32_u24_e32 v13, 0xfe00, v12
	v_sub_u32_e32 v13, v10, v13
	v_lshlrev_b32_e32 v12, 20, v12
	v_lshl_add_u32 v10, v13, 4, v12
	global_load_dwordx4 v[56:59], v10, s[10:11]
	v_lshrrev_b32_e32 v12, 9, v11
	v_mul_hi_u32 v12, v12, s3
	v_mul_u32_u24_e32 v13, 0xfe00, v12
	v_sub_u32_e32 v13, v11, v13
	v_lshlrev_b32_e32 v12, 20, v12
	v_lshl_add_u32 v11, v13, 4, v12
	global_load_dwordx4 v[60:63], v11, s[10:11]
	s_waitcnt vmcnt(0)
	global_store_dwordx4 v4, v[32:35], s[6:7]
	global_store_dwordx4 v5, v[36:39], s[6:7]
	global_store_dwordx4 v6, v[40:43], s[6:7]
	global_store_dwordx4 v7, v[44:47], s[6:7]
	global_store_dwordx4 v8, v[48:51], s[6:7]
	global_store_dwordx4 v9, v[52:55], s[6:7]
	global_store_dwordx4 v10, v[56:59], s[6:7]
	global_store_dwordx4 v11, v[60:63], s[6:7]
	s_nop 1
	v_min_u32_e32 v4, s12, v2
	v_add_u32_e32 v2, s8, v2
	v_min_u32_e32 v5, s12, v2
	v_add_u32_e32 v2, s8, v2
	v_min_u32_e32 v6, s12, v2
	v_add_u32_e32 v2, s8, v2
	v_min_u32_e32 v7, s12, v2
	v_add_u32_e32 v2, s8, v2
	v_min_u32_e32 v8, s12, v2
	v_add_u32_e32 v2, s8, v2
	v_min_u32_e32 v9, s12, v2
	v_add_u32_e32 v2, s8, v2
	v_min_u32_e32 v10, s12, v2
	v_add_u32_e32 v2, s8, v2
	v_lshrrev_b32_e32 v12, 9, v4
	v_mul_hi_u32 v12, v12, s3
	v_mul_u32_u24_e32 v13, 0xfe00, v12
	v_sub_u32_e32 v13, v4, v13
	v_lshlrev_b32_e32 v12, 20, v12
	v_lshl_add_u32 v4, v13, 4, v12
	global_load_dwordx4 v[32:35], v4, s[10:11]
	v_lshrrev_b32_e32 v12, 9, v5
	v_mul_hi_u32 v12, v12, s3
	v_mul_u32_u24_e32 v13, 0xfe00, v12
	v_sub_u32_e32 v13, v5, v13
	v_lshlrev_b32_e32 v12, 20, v12
	v_lshl_add_u32 v5, v13, 4, v12
	global_load_dwordx4 v[36:39], v5, s[10:11]
	v_lshrrev_b32_e32 v12, 9, v6
	v_mul_hi_u32 v12, v12, s3
	v_mul_u32_u24_e32 v13, 0xfe00, v12
	v_sub_u32_e32 v13, v6, v13
	v_lshlrev_b32_e32 v12, 20, v12
	v_lshl_add_u32 v6, v13, 4, v12
	global_load_dwordx4 v[40:43], v6, s[10:11]
	v_lshrrev_b32_e32 v12, 9, v7
	v_mul_hi_u32 v12, v12, s3
	v_mul_u32_u24_e32 v13, 0xfe00, v12
	v_sub_u32_e32 v13, v7, v13
	v_lshlrev_b32_e32 v12, 20, v12
	v_lshl_add_u32 v7, v13, 4, v12
	global_load_dwordx4 v[44:47], v7, s[10:11]
	v_lshrrev_b32_e32 v12, 9, v8
	v_mul_hi_u32 v12, v12, s3
	v_mul_u32_u24_e32 v13, 0xfe00, v12
	v_sub_u32_e32 v13, v8, v13
	v_lshlrev_b32_e32 v12, 20, v12
	v_lshl_add_u32 v8, v13, 4, v12
	global_load_dwordx4 v[48:51], v8, s[10:11]
	v_lshrrev_b32_e32 v12, 9, v9
	v_mul_hi_u32 v12, v12, s3
	v_mul_u32_u24_e32 v13, 0xfe00, v12
	v_sub_u32_e32 v13, v9, v13
	v_lshlrev_b32_e32 v12, 20, v12
	v_lshl_add_u32 v9, v13, 4, v12
	global_load_dwordx4 v[52:55], v9, s[10:11]
	v_lshrrev_b32_e32 v12, 9, v10
	v_mul_hi_u32 v12, v12, s3
	v_mul_u32_u24_e32 v13, 0xfe00, v12
	v_sub_u32_e32 v13, v10, v13
	v_lshlrev_b32_e32 v12, 20, v12
	v_lshl_add_u32 v10, v13, 4, v12
	global_load_dwordx4 v[56:59], v10, s[10:11]
	s_waitcnt vmcnt(0)
	global_store_dwordx4 v4, v[32:35], s[6:7]
	global_store_dwordx4 v5, v[36:39], s[6:7]
	global_store_dwordx4 v6, v[40:43], s[6:7]
	global_store_dwordx4 v7, v[44:47], s[6:7]
	global_store_dwordx4 v8, v[48:51], s[6:7]
	global_store_dwordx4 v9, v[52:55], s[6:7]
	global_store_dwordx4 v10, v[56:59], s[6:7]
	s_nop 1
	v_readlane_b32 s2, v200, 0
	v_readlane_b32 s3, v200, 1
	v_readlane_b32 s4, v200, 2
	v_readlane_b32 s5, v200, 3
	v_readlane_b32 s6, v200, 4
	v_readlane_b32 s7, v200, 5
	v_readlane_b32 s8, v200, 6
	v_readlane_b32 s9, v200, 7
	v_readlane_b32 s10, v200, 8
	v_readlane_b32 s11, v200, 9
	v_readlane_b32 s12, v200, 10
	v_readlane_b32 s13, v200, 11
	v_readlane_b32 s14, v200, 12
	v_readlane_b32 s15, v200, 13

.LBB0_2040:
	s_waitcnt vmcnt(0)
	s_barrier
	v_readlane_b32 s100, v254, 43
	v_readlane_b32 s101, v254, 19
	s_cmp_lg_u32 s100, 0
	s_cbranch_scc1 .Lcv2_skip
	s_cmpk_lt_u32 s101, 32
	s_cbranch_scc1 .Lcv2_skip
	v_writelane_b32 v200, s2, 0
	v_writelane_b32 v200, s3, 1
	v_writelane_b32 v200, s4, 2
	v_writelane_b32 v200, s5, 3
	v_writelane_b32 v200, s6, 4
	v_writelane_b32 v200, s7, 5
	v_writelane_b32 v200, s8, 6
	v_writelane_b32 v200, s9, 7
	v_writelane_b32 v200, s10, 8
	v_writelane_b32 v200, s11, 9
	v_writelane_b32 v200, s12, 10
	v_writelane_b32 v200, s13, 11
	v_writelane_b32 v200, s14, 12
	v_writelane_b32 v200, s15, 13
	v_writelane_b32 v200, s16, 14
	v_writelane_b32 v200, s17, 15
	v_writelane_b32 v200, s18, 16
	v_writelane_b32 v200, s19, 17
	v_writelane_b32 v200, s20, 18
	v_writelane_b32 v200, s21, 19
	v_writelane_b32 v200, s22, 20
	v_writelane_b32 v200, s23, 21
	v_writelane_b32 v200, s24, 22
	v_writelane_b32 v200, s25, 23
	v_writelane_b32 v200, s26, 24
	v_writelane_b32 v200, s27, 25
	v_writelane_b32 v200, s28, 26
	v_writelane_b32 v200, s29, 27
	v_writelane_b32 v200, s30, 28
	v_writelane_b32 v200, s31, 29
	v_writelane_b32 v200, s32, 30
	v_writelane_b32 v200, s33, 31
	v_writelane_b32 v200, s34, 32
	v_writelane_b32 v200, s35, 33
	v_writelane_b32 v200, s36, 34
	v_writelane_b32 v200, s37, 35
	v_writelane_b32 v200, s38, 36
	v_writelane_b32 v200, s39, 37
	v_writelane_b32 v200, s40, 38
	v_writelane_b32 v200, s41, 39
	v_writelane_b32 v200, s42, 40
	v_writelane_b32 v200, s43, 41
	v_writelane_b32 v200, s44, 42
	v_writelane_b32 v200, s45, 43
	v_writelane_b32 v200, s46, 44
	v_writelane_b32 v200, s47, 45
	v_writelane_b32 v200, s48, 46
	v_writelane_b32 v200, s49, 47
	v_writelane_b32 v200, s50, 48
	v_writelane_b32 v200, s51, 49
	v_writelane_b32 v200, s52, 50
	v_writelane_b32 v200, s53, 51
	v_writelane_b32 v200, s54, 52
	v_writelane_b32 v200, s55, 53
	v_writelane_b32 v200, s56, 54
	v_writelane_b32 v200, s57, 55
	v_writelane_b32 v200, s58, 56
	v_writelane_b32 v200, s59, 57
	v_writelane_b32 v200, s60, 58
	v_writelane_b32 v200, s61, 59
	v_writelane_b32 v200, s62, 60
	v_writelane_b32 v200, s63, 61
	v_writelane_b32 v200, s64, 62
	v_writelane_b32 v200, s65, 63
	v_writelane_b32 v201, s66, 0
	v_writelane_b32 v201, s67, 1
	v_writelane_b32 v201, s68, 2
	v_writelane_b32 v201, s69, 3
	v_writelane_b32 v201, s70, 4
	v_writelane_b32 v201, s71, 5
	v_writelane_b32 v201, s72, 6
	v_writelane_b32 v201, s73, 7
	v_writelane_b32 v201, s74, 8
	v_writelane_b32 v201, s75, 9
	v_writelane_b32 v201, s76, 10
	v_writelane_b32 v201, s77, 11
	v_writelane_b32 v201, s78, 12
	v_writelane_b32 v201, s79, 13
	v_writelane_b32 v201, s80, 14
	v_writelane_b32 v201, s81, 15
	v_writelane_b32 v201, s82, 16
	v_writelane_b32 v201, s83, 17
	v_writelane_b32 v201, s84, 18
	v_writelane_b32 v201, s85, 19
	v_writelane_b32 v201, s86, 20
	v_writelane_b32 v201, s87, 21
	v_writelane_b32 v201, s88, 22
	v_writelane_b32 v201, s89, 23
	v_writelane_b32 v201, s90, 24
	v_writelane_b32 v201, s91, 25
	v_writelane_b32 v201, s92, 26
	v_writelane_b32 v201, s93, 27
	v_writelane_b32 v201, s94, 28
	v_writelane_b32 v201, s95, 29
	v_writelane_b32 v201, s96, 30
	v_writelane_b32 v201, s97, 31
	v_writelane_b32 v201, s98, 32
	v_writelane_b32 v201, s99, 33
	s_load_dwordx4 s[88:91], s[0:1], 0xb8
	v_mbcnt_lo_u32_b32 v0, -1, 0
	v_mbcnt_hi_u32_b32 v0, -1, v0
	v_readlane_b32 s87, v255, 4
	s_waitcnt lgkmcnt(0)
	v_and_b32_e32 v21, 31, v0
	v_bfe_u32 v31, v0, 5, 1
	v_lshlrev_b32_e32 v2, 2, v21
	v_mul_u32_u24_e32 v3, 0x84, v31
	v_bfe_u32 v29, v0, 3, 3
	s_lshl_b32 s2, s87, 14
	s_add_i32 s3, s2, 0
	v_add3_u32 v28, s3, v2, v3
	v_lshlrev_b32_e32 v2, 3, v0
	v_and_b32_e32 v2, 56, v2
	v_mul_u32_u24_e32 v4, 0x84, v2
	v_lshlrev_b32_e32 v5, 2, v29
	s_mov_b32 s7, 0
	v_mov_b32_e32 v3, 0
	v_add3_u32 v30, s3, v4, v5
	v_lshlrev_b32_e32 v18, 1, v2
	s_sub_i32 s2, s101, 32
	s_lshl_b32 s2, s2, 3
	s_add_i32 s2, s2, s87
	s_addk_i32 s2, 0x3000
	s_movk_i32 s43, 0x700
	s_movk_i32 s100, 0x37ff
	s_mov_b32 s101, 2
	s_branch .Lcv_relay_fwd
.Lcv2_ret:
	s_cmp_eq_u32 s101, 3
	s_cbranch_scc1 .Lcv2_done
	v_readlane_b32 s2, v254, 19
	v_readlane_b32 s87, v255, 4
	s_sub_i32 s2, s2, 32
	s_lshl_b32 s2, s2, 3
	s_add_i32 s2, s2, s87
	s_addk_i32 s2, 0x780
	s_movk_i32 s43, 0x700
	s_movk_i32 s100, 0xfff
	s_mov_b32 s101, 3
	s_mov_b32 s7, 0
	s_branch .Lcv_relay_fwd
